# G3b EpiGate8 epilogue: the two column-constant load groups (bj=0/1) issued with the ssq loads into dead K-loop fragment registers; removes two exposed load latencies and the store-ack wait per tile; o
# baseline (speedup 1.0000x reference)
; __device__ __forceinline__ void row_rstd(const unsigned long long* ssq, int row0, float (&rs)[2][4]) {
;     unsigned long long q[2][4];
; #pragma unroll
;     for (int ai = 0; ai < 2; ++ai)
; #pragma unroll
;         for (int m = 0; m < 4; ++m) q[ai][m] = ssq[row0 + ai * HALF + m * 16];
;     asm volatile("" : "+v"(q[0][0]), "+v"(q[0][1]), "+v"(q[0][2]), "+v"(q[0][3]), "+v"(q[1][0]), "+v"(q[1][1]), "+v"(q[1][2]), "+v"(q[1][3]));
; #pragma unroll
;     for (int ai = 0; ai < 2; ++ai)
; #pragma unroll
;         for (int m = 0; m < 4; ++m) {
;             const float qf = __builtin_fmaf((float)(unsigned)(q[ai][m] >> 32), 4294967296.0f, (float)(unsigned)q[ai][m]);
;             rs[ai][m] = __builtin_amdgcn_rsqf(__builtin_fmaf(qf, 1.0f / (SSQ_SCALE * DM), EPS)); }
; }
;     template <int QVV> __device__ __forceinline__ void run(f32x4 (&acc)[2][2][4][2], const Unit& u, int wr, int wc, int fr, int fq) const {
;         constexpr int nai = (QVV == 2) ? 1 : 2; const int r0 = u.pm * BM + (QVV == 2 ? (u.seg - 1) * HALF : 0);
;         char* tb = (char*)(O + (size_t)r0 * NGC + u.pn * BM);
;         const int v = u.pm < 4 ? 4 : ((u.pm - 4) >> 5);
;         const char* swb = (const char*)(sw + (size_t)v * SWLD + u.pn * BM); const char* bmb = (const char*)(bm + u.pn * BM);
;         unsigned lo = (unsigned)((wr * 64 + fr) * NGC + wc * 32 + 8 * fq);
;         unsigned co = (unsigned)(wc * 32 + 8 * fq) * 4u;
;         asm volatile("" : "+v"(lo), "+v"(co));
;         float rs[2][4]; row_rstd(ssq, r0 + wr * 64 + fr, rs);
; #pragma unroll
;         for (int bj = 0; bj < 2; ++bj) {
;             const f32x4 s0 = (*(const f32x4*)(swb + co + bj * HALF * 4) + *(const f32x4*)(bmb + co + bj * HALF * 4)) * (-LOG2E) - 7.994353436858858f,
;                         s1 = (*(const f32x4*)(swb + co + bj * HALF * 4 + 16) + *(const f32x4*)(bmb + co + bj * HALF * 4 + 16)) * (-LOG2E) - 7.994353436858858f;
.LBB0_1279:
	s_mul_i32 s98, s53, 24
	s_add_i32 s98, s98, s52
	s_lshl_b32 s98, s98, 16
	s_add_u32 s98, s1, s98
	s_addc_u32 s99, s2, 0
	s_lshl_b32 s67, s53, 8
	v_add_u32_e32 v130, s67, v154
	v_ashrrev_i32_e32 v131, 31, v130
	v_and_b32_e32 v146, 0x1c0, v0
	v_lshlrev_b32_e32 v146, 7, v146
	v_and_b32_e32 v148, 48, v0
	v_lshl_or_b32 v146, v148, 4, v146
	v_and_b32_e32 v148, 15, v0
	v_lshl_or_b32 v146, v148, 3, v146
	v_mov_b32_e32 v159, v156
	v_lshl_add_u64 v[130:131], v[130:131], 3, s[44:45]
	global_load_dwordx2 v[132:133], v[130:131], off
	global_load_dwordx2 v[134:135], v[130:131], off offset:128
	global_load_dwordx2 v[136:137], v[130:131], off offset:256
	global_load_dwordx2 v[138:139], v[130:131], off offset:384
	global_load_dwordx2 v[140:141], v[130:131], off offset:1024
	global_load_dwordx2 v[142:143], v[130:131], off offset:1152
	global_load_dwordx2 v[144:145], v[130:131], off offset:1280
	s_nop 0
	global_load_dwordx2 v[130:131], v[130:131], off offset:1408
	s_mul_i32 s42, s53, 0x180000
	s_mul_hi_i32 s43, s67, 0x1800
	s_add_u32 s42, s1, s42
	s_addc_u32 s43, s2, s43
	s_lshl_b32 s52, s52, 8
	s_ashr_i32 s53, s52, 31
	s_add_u32 s42, s42, s52
	s_addc_u32 s43, s43, s53
	s_lshl_b64 s[30:31], s[30:31], 2
	s_add_u32 s62, s7, s30
	s_addc_u32 s63, s9, s31
	s_lshl_b64 s[30:31], s[52:53], 2
	s_add_u32 s62, s62, s30
	s_addc_u32 s63, s63, s31
	s_add_u32 s52, s3, s30
	s_flbit_i32_b32 s30, 0
	s_addc_u32 s53, s5, s31
	s_min_u32 s30, s30, 32
	s_sub_i32 s31, 32, s30
	global_load_dwordx4 v[182:185], v159, s[62:63] offset:16
	global_load_dwordx4 v[186:189], v159, s[62:63]
	global_load_dwordx4 v[190:193], v159, s[52:53] offset:16
	global_load_dwordx4 v[194:197], v159, s[52:53]
	global_load_dwordx4 v[198:201], v159, s[62:63] offset:528
	global_load_dwordx4 v[202:205], v159, s[62:63] offset:512
	global_load_dwordx4 v[206:209], v159, s[52:53] offset:528
	global_load_dwordx4 v[210:213], v159, s[52:53] offset:512
	v_mov_b32_e32 v147, v175
	s_waitcnt vmcnt(8)
	s_nop 0
	v_mov_b32_e32 v174, v133
	v_lshlrev_b64 v[148:149], s30, v[174:175]
	v_min_u32_e32 v133, 1, v148
	v_or_b32_e32 v133, v149, v133
	v_cvt_f32_u32_e32 v133, v133
	v_cvt_f32_u32_e32 v132, v132
	v_mov_b32_e32 v174, v135
	v_cvt_f32_u32_e32 v130, v130
	v_ldexp_f32 v133, v133, s31
	v_fmac_f32_e32 v132, 0x4f800000, v133
	v_fmamk_f32 v132, v132, 0x30000000, v231
	v_rsq_f32_e32 v168, v132
	v_lshlrev_b64 v[132:133], s30, v[174:175]
	v_min_u32_e32 v132, 1, v132
	v_or_b32_e32 v132, v133, v132
	v_cvt_f32_u32_e32 v132, v132
	v_cvt_f32_u32_e32 v133, v134
	v_mov_b32_e32 v174, v137
	v_lshl_add_u64 v[148:149], s[98:99], 0, v[146:147]
	v_ldexp_f32 v132, v132, s31
	v_fmac_f32_e32 v133, 0x4f800000, v132
	v_fmamk_f32 v132, v133, 0x30000000, v231
	v_rsq_f32_e32 v167, v132
	v_lshlrev_b64 v[132:133], s30, v[174:175]
	v_min_u32_e32 v132, 1, v132
	v_or_b32_e32 v132, v133, v132
	v_cvt_f32_u32_e32 v132, v132
	v_cvt_f32_u32_e32 v133, v136
	v_mov_b32_e32 v174, v139
	v_mul_f32_e32 v147, 0xbfb8aa3b, v168
	v_ldexp_f32 v132, v132, s31
	v_fmac_f32_e32 v133, 0x4f800000, v132
	v_fmamk_f32 v132, v133, 0x30000000, v231
	v_rsq_f32_e32 v166, v132
	v_lshlrev_b64 v[132:133], s30, v[174:175]
	v_min_u32_e32 v132, 1, v132
	v_or_b32_e32 v132, v133, v132
	v_cvt_f32_u32_e32 v132, v132
	v_cvt_f32_u32_e32 v133, v138
	v_mov_b32_e32 v174, v141
	v_ldexp_f32 v132, v132, s31
	v_fmac_f32_e32 v133, 0x4f800000, v132
	v_fmamk_f32 v132, v133, 0x30000000, v231
	v_rsq_f32_e32 v165, v132
	v_lshlrev_b64 v[132:133], s30, v[174:175]
	v_min_u32_e32 v132, 1, v132
	v_or_b32_e32 v132, v133, v132
	v_cvt_f32_u32_e32 v132, v132
	v_cvt_f32_u32_e32 v133, v140
	v_mov_b32_e32 v174, v143
	v_ldexp_f32 v132, v132, s31
	v_fmac_f32_e32 v133, 0x4f800000, v132
	v_fmamk_f32 v132, v133, 0x30000000, v231
	v_rsq_f32_e32 v164, v132
	v_lshlrev_b64 v[132:133], s30, v[174:175]
	v_min_u32_e32 v132, 1, v132
	v_or_b32_e32 v132, v133, v132
	v_cvt_f32_u32_e32 v132, v132
	v_cvt_f32_u32_e32 v133, v142
	v_mov_b32_e32 v174, v145
	v_ldexp_f32 v132, v132, s31
	v_fmac_f32_e32 v133, 0x4f800000, v132
	v_fmamk_f32 v132, v133, 0x30000000, v231
	v_rsq_f32_e32 v163, v132
	v_lshlrev_b64 v[132:133], s30, v[174:175]
	v_min_u32_e32 v132, 1, v132
	v_or_b32_e32 v132, v133, v132
	v_cvt_f32_u32_e32 v132, v132
	v_cvt_f32_u32_e32 v133, v144
	v_mov_b32_e32 v174, v131
	v_ldexp_f32 v132, v132, s31
	v_fmac_f32_e32 v133, 0x4f800000, v132
	v_fmamk_f32 v132, v133, 0x30000000, v231
	v_rsq_f32_e32 v161, v132
	v_lshlrev_b64 v[132:133], s30, v[174:175]
	v_min_u32_e32 v131, 1, v132
	v_or_b32_e32 v131, v133, v131
	v_cvt_f32_u32_e32 v131, v131
	s_mov_b32 s30, 0x400
	v_ldexp_f32 v131, v131, s31
	v_fmac_f32_e32 v130, 0x4f800000, v131
	v_fmamk_f32 v130, v130, 0x30000000, v231
	v_rsq_f32_e32 v160, v130
	s_waitcnt vmcnt(4)
;     template <int QVV> __device__ __forceinline__ void run(f32x4 (&acc)[2][2][4][2], const Unit& u, int wr, int wc, int fr, int fq) const {
;     ...
;             const f32x4 s0 = (*(const f32x4*)(swb + co + bj * HALF * 4) + *(const f32x4*)(bmb + co + bj * HALF * 4)) * (-LOG2E) - 7.994353436858858f,
;                         s1 = (*(const f32x4*)(swb + co + bj * HALF * 4 + 16) + *(const f32x4*)(bmb + co + bj * HALF * 4 + 16)) * (-LOG2E) - 7.994353436858858f;
; #pragma unroll
;             for (int ai = 0; ai < 2; ++ai)
; #pragma unroll
;                 for (int m = 0; m < 4; ++m) { if (ai >= nai) continue;
;                     const float rn = rs[ai][m] * (-LOG2E);
;                     const f32x4 x0 = acc[ai][bj][m][0] * rn + s0, x1 = acc[ai][bj][m][1] * rn + s1;
;                     f32x4 d0, d1;
; #pragma unroll
;                     for (int i = 0; i < 4; ++i) { d0[i] = __builtin_amdgcn_exp2f(x0[i]); d1[i] = __builtin_amdgcn_exp2f(x1[i]); }
;                     d0 = d0 + (1.0f / 255.0f); d1 = d1 + (1.0f / 255.0f);
;                     u32x2 w = {0u, 0u};
; #pragma unroll
;                     for (int i = 0; i < 4; ++i) { const float g0 = fmaxf(__builtin_amdgcn_rcpf(d0[i]), 1.0f), g1 = fmaxf(__builtin_amdgcn_rcpf(d1[i]), 1.0f);
;                         w.x = __builtin_amdgcn_cvt_pk_u8_f32(g0, i, w.x); w.y = __builtin_amdgcn_cvt_pk_u8_f32(g1, i, w.y); }
;                     *(u32x2*)(tb + lo + (unsigned)((ai * HALF + m * 16) * NGC + bj * HALF)) = w; }
	v_mov_b64_e32 v[130:131], v[182:183]
	v_mov_b64_e32 v[132:133], v[184:185]
	v_mov_b64_e32 v[138:139], v[186:187]
	v_mov_b64_e32 v[140:141], v[188:189]
	v_mov_b64_e32 v[134:135], v[190:191]
	v_mov_b64_e32 v[136:137], v[192:193]
	v_mov_b64_e32 v[142:143], v[194:195]
	v_mov_b64_e32 v[144:145], v[196:197]
	v_add_f32_e32 v138, v138, v142
	v_fmamk_f32 v138, v138, 0xbfb8aa3b, v236
	v_fma_f32 v126, v126, v147, v138
	v_exp_f32_e32 v142, v126
	v_add_f32_e32 v126, v130, v134
	v_fmamk_f32 v126, v126, 0xbfb8aa3b, v236
	v_fma_f32 v122, v122, v147, v126
	v_exp_f32_e32 v134, v122
	v_add_f32_e32 v122, v139, v143
	v_fmamk_f32 v130, v122, 0xbfb8aa3b, v236
	v_fma_f32 v122, v127, v147, v130
	v_exp_f32_e32 v143, v122
	v_add_f32_e32 v122, v131, v135
	v_fmamk_f32 v127, v122, 0xbfb8aa3b, v236
	v_fma_f32 v122, v123, v147, v127
	v_exp_f32_e32 v135, v122
	v_add_f32_e32 v122, v140, v144
	v_fmamk_f32 v123, v122, 0xbfb8aa3b, v236
	v_fma_f32 v122, v128, v147, v123
	v_exp_f32_e32 v140, v122
	v_add_f32_e32 v122, v132, v136
	v_fmamk_f32 v128, v122, 0xbfb8aa3b, v236
	v_fma_f32 v122, v124, v147, v128
	v_exp_f32_e32 v132, v122
	v_add_f32_e32 v122, v141, v145
	v_fmamk_f32 v124, v122, 0xbfb8aa3b, v236
	v_fma_f32 v122, v129, v147, v124
	v_exp_f32_e32 v141, v122
	v_add_f32_e32 v122, v133, v137
	v_fmamk_f32 v129, v122, 0xbfb8aa3b, v236
	v_fma_f32 v122, v125, v147, v129
	v_pk_add_f32 v[136:137], v[140:141], s[0:1] op_sel_hi:[1,0]
	v_pk_add_f32 v[140:141], v[142:143], s[0:1] op_sel_hi:[1,0]
	v_exp_f32_e32 v133, v122
	v_rcp_f32_e32 v122, v140
	v_rcp_f32_e32 v131, v141
	v_pk_add_f32 v[134:135], v[134:135], s[0:1] op_sel_hi:[1,0]
	v_pk_add_f32 v[132:133], v[132:133], s[0:1] op_sel_hi:[1,0]
	v_max_f32_e32 v122, 1.0, v122
	v_rcp_f32_e32 v125, v134
	v_cvt_pk_u8_f32 v122, v122, 0, 0
	v_max_f32_e32 v131, 1.0, v131
	v_rcp_f32_e32 v134, v135
	v_cvt_pk_u8_f32 v122, v131, 1, v122
	v_rcp_f32_e32 v131, v136
	v_rcp_f32_e32 v132, v132
	v_max_f32_e32 v125, 1.0, v125
	v_cvt_pk_u8_f32 v125, v125, 0, 0
	v_max_f32_e32 v134, 1.0, v134
	v_max_f32_e32 v131, 1.0, v131
	v_cvt_pk_u8_f32 v125, v134, 1, v125
	v_max_f32_e32 v132, 1.0, v132
	v_cvt_pk_u8_f32 v122, v131, 2, v122
	v_rcp_f32_e32 v131, v137
	v_cvt_pk_u8_f32 v125, v132, 2, v125
	v_rcp_f32_e32 v132, v133
	v_max_f32_e32 v131, 1.0, v131
	v_max_f32_e32 v133, 1.0, v132
	v_cvt_pk_u8_f32 v132, v131, 3, v122
	v_mul_f32_e32 v122, 0xbfb8aa3b, v167
	v_fma_f32 v114, v114, v122, v126
	v_fma_f32 v115, v115, v122, v127
	v_exp_f32_e32 v114, v114
	v_exp_f32_e32 v115, v115
	v_fma_f32 v116, v116, v122, v128
	v_fma_f32 v117, v117, v122, v129
	v_exp_f32_e32 v116, v116
	v_exp_f32_e32 v117, v117
	v_fma_f32 v118, v118, v122, v138
	v_fma_f32 v119, v119, v122, v130
	v_exp_f32_e32 v118, v118
	v_exp_f32_e32 v119, v119
	v_pk_add_f32 v[114:115], v[114:115], s[0:1] op_sel_hi:[1,0]
	v_fma_f32 v120, v120, v122, v123
	v_fma_f32 v121, v121, v122, v124
	v_rcp_f32_e32 v114, v114
	v_exp_f32_e32 v120, v120
	v_exp_f32_e32 v121, v121
	v_pk_add_f32 v[116:117], v[116:117], s[0:1] op_sel_hi:[1,0]
	v_rcp_f32_e32 v115, v115
	v_rcp_f32_e32 v116, v116
	v_pk_add_f32 v[118:119], v[118:119], s[0:1] op_sel_hi:[1,0]
	v_max_f32_e32 v114, 1.0, v114
	v_rcp_f32_e32 v118, v118
	v_pk_add_f32 v[120:121], v[120:121], s[0:1] op_sel_hi:[1,0]
	v_cvt_pk_u8_f32 v114, v114, 0, 0
	v_rcp_f32_e32 v119, v119
	v_max_f32_e32 v115, 1.0, v115
	v_cvt_pk_u8_f32 v114, v115, 1, v114
	v_rcp_f32_e32 v115, v120
	v_max_f32_e32 v116, 1.0, v116
	v_rcp_f32_e32 v117, v117
	v_cvt_pk_u8_f32 v114, v116, 2, v114
	v_rcp_f32_e32 v116, v121
	v_max_f32_e32 v118, 1.0, v118
	v_cvt_pk_u8_f32 v118, v118, 0, 0
	v_max_f32_e32 v119, 1.0, v119
	v_cvt_pk_u8_f32 v118, v119, 1, v118
	v_max_f32_e32 v115, 1.0, v115
	v_max_f32_e32 v117, 1.0, v117
	v_cvt_pk_u8_f32 v115, v115, 2, v118
	v_max_f32_e32 v116, 1.0, v116
	v_cvt_pk_u8_f32 v117, v117, 3, v114
	v_add_co_u32_e32 v114, vcc, s30, v148
	v_cvt_pk_u8_f32 v116, v116, 3, v115
	s_nop 0
	v_addc_co_u32_e32 v115, vcc, 0, v149, vcc
	global_store_dwordx2 v[114:115], v[116:117], off
	v_mul_f32_e32 v116, 0xbfb8aa3b, v166
	v_fma_f32 v106, v106, v116, v126
	v_fma_f32 v107, v107, v116, v127
	v_exp_f32_e32 v106, v106
	v_exp_f32_e32 v107, v107
	v_fma_f32 v108, v108, v116, v128
	v_fma_f32 v109, v109, v116, v129
	v_exp_f32_e32 v108, v108
	v_exp_f32_e32 v109, v109
	v_fma_f32 v110, v110, v116, v138
	v_fma_f32 v111, v111, v116, v130
	v_exp_f32_e32 v110, v110
	v_exp_f32_e32 v111, v111
	v_pk_add_f32 v[106:107], v[106:107], s[0:1] op_sel_hi:[1,0]
	v_fma_f32 v112, v112, v116, v123
	v_fma_f32 v113, v113, v116, v124
	v_rcp_f32_e32 v106, v106
	v_exp_f32_e32 v112, v112
	v_exp_f32_e32 v113, v113
	v_pk_add_f32 v[108:109], v[108:109], s[0:1] op_sel_hi:[1,0]
	v_rcp_f32_e32 v107, v107
	v_rcp_f32_e32 v108, v108
	v_pk_add_f32 v[110:111], v[110:111], s[0:1] op_sel_hi:[1,0]
	v_max_f32_e32 v106, 1.0, v106
	v_rcp_f32_e32 v110, v110
	v_pk_add_f32 v[112:113], v[112:113], s[0:1] op_sel_hi:[1,0]
	v_cvt_pk_u8_f32 v106, v106, 0, 0
	v_rcp_f32_e32 v111, v111
	v_max_f32_e32 v107, 1.0, v107
	v_cvt_pk_u8_f32 v106, v107, 1, v106
	v_rcp_f32_e32 v107, v112
	v_max_f32_e32 v108, 1.0, v108
	v_rcp_f32_e32 v109, v109
	v_cvt_pk_u8_f32 v106, v108, 2, v106
	v_rcp_f32_e32 v108, v113
	v_max_f32_e32 v110, 1.0, v110
	v_cvt_pk_u8_f32 v110, v110, 0, 0
	v_max_f32_e32 v111, 1.0, v111
	v_cvt_pk_u8_f32 v110, v111, 1, v110
	v_max_f32_e32 v107, 1.0, v107
	v_max_f32_e32 v109, 1.0, v109
	s_mov_b32 s30, 0x800
	v_cvt_pk_u8_f32 v107, v107, 2, v110
	v_max_f32_e32 v108, 1.0, v108
	v_cvt_pk_u8_f32 v109, v109, 3, v106
	v_add_co_u32_e32 v106, vcc, s30, v148
	v_cvt_pk_u8_f32 v108, v108, 3, v107
	s_nop 0
	v_addc_co_u32_e32 v107, vcc, 0, v149, vcc
	global_store_dwordx2 v[106:107], v[108:109], off
;     template <int QVV> __device__ __forceinline__ void run(f32x4 (&acc)[2][2][4][2], const Unit& u, int wr, int wc, int fr, int fq) const {
;     ...
;             for (int ai = 0; ai < 2; ++ai)
; #pragma unroll
;                 for (int m = 0; m < 4; ++m) { if (ai >= nai) continue;
;                     const float rn = rs[ai][m] * (-LOG2E);
;                     const f32x4 x0 = acc[ai][bj][m][0] * rn + s0, x1 = acc[ai][bj][m][1] * rn + s1;
;                     f32x4 d0, d1;
; #pragma unroll
;                     for (int i = 0; i < 4; ++i) { d0[i] = __builtin_amdgcn_exp2f(x0[i]); d1[i] = __builtin_amdgcn_exp2f(x1[i]); }
;                     d0 = d0 + (1.0f / 255.0f); d1 = d1 + (1.0f / 255.0f);
;                     u32x2 w = {0u, 0u};
; #pragma unroll
;                     for (int i = 0; i < 4; ++i) { const float g0 = fmaxf(__builtin_amdgcn_rcpf(d0[i]), 1.0f), g1 = fmaxf(__builtin_amdgcn_rcpf(d1[i]), 1.0f);
;                         w.x = __builtin_amdgcn_cvt_pk_u8_f32(g0, i, w.x); w.y = __builtin_amdgcn_cvt_pk_u8_f32(g1, i, w.y); }
;                     *(u32x2*)(tb + lo + (unsigned)((ai * HALF + m * 16) * NGC + bj * HALF)) = w; }
	v_mul_f32_e32 v108, 0xbfb8aa3b, v165
	v_fma_f32 v98, v98, v108, v126
	v_fma_f32 v99, v99, v108, v127
	v_exp_f32_e32 v98, v98
	v_exp_f32_e32 v99, v99
	v_fma_f32 v100, v100, v108, v128
	v_fma_f32 v101, v101, v108, v129
	v_exp_f32_e32 v100, v100
	v_exp_f32_e32 v101, v101
	v_fma_f32 v102, v102, v108, v138
	v_fma_f32 v103, v103, v108, v130
	v_exp_f32_e32 v102, v102
	v_exp_f32_e32 v103, v103
	v_pk_add_f32 v[98:99], v[98:99], s[0:1] op_sel_hi:[1,0]
	v_fma_f32 v104, v104, v108, v123
	v_fma_f32 v105, v105, v108, v124
	v_rcp_f32_e32 v98, v98
	v_exp_f32_e32 v104, v104
	v_exp_f32_e32 v105, v105
	v_pk_add_f32 v[100:101], v[100:101], s[0:1] op_sel_hi:[1,0]
	v_rcp_f32_e32 v99, v99
	v_rcp_f32_e32 v100, v100
	v_pk_add_f32 v[102:103], v[102:103], s[0:1] op_sel_hi:[1,0]
	v_max_f32_e32 v98, 1.0, v98
	v_rcp_f32_e32 v102, v102
	v_pk_add_f32 v[104:105], v[104:105], s[0:1] op_sel_hi:[1,0]
	v_cvt_pk_u8_f32 v98, v98, 0, 0
	v_rcp_f32_e32 v103, v103
	v_max_f32_e32 v99, 1.0, v99
	v_cvt_pk_u8_f32 v98, v99, 1, v98
	v_rcp_f32_e32 v99, v104
	v_max_f32_e32 v100, 1.0, v100
	v_rcp_f32_e32 v101, v101
	v_cvt_pk_u8_f32 v98, v100, 2, v98
	v_rcp_f32_e32 v100, v105
	v_max_f32_e32 v102, 1.0, v102
	v_cvt_pk_u8_f32 v102, v102, 0, 0
	v_max_f32_e32 v103, 1.0, v103
	v_cvt_pk_u8_f32 v102, v103, 1, v102
	v_max_f32_e32 v99, 1.0, v99
	v_max_f32_e32 v101, 1.0, v101
	s_mov_b32 s30, 0xc00
	v_cvt_pk_u8_f32 v99, v99, 2, v102
	v_max_f32_e32 v100, 1.0, v100
	v_cvt_pk_u8_f32 v101, v101, 3, v98
	v_add_co_u32_e32 v98, vcc, s30, v148
	v_cvt_pk_u8_f32 v100, v100, 3, v99
	s_nop 0
	v_addc_co_u32_e32 v99, vcc, 0, v149, vcc
	global_store_dwordx2 v[98:99], v[100:101], off
	v_mul_f32_e32 v100, 0xbfb8aa3b, v164
	v_fma_f32 v90, v90, v100, v126
	v_fma_f32 v91, v91, v100, v127
	v_exp_f32_e32 v90, v90
	v_exp_f32_e32 v91, v91
	v_fma_f32 v92, v92, v100, v128
	v_fma_f32 v93, v93, v100, v129
	v_exp_f32_e32 v92, v92
	v_exp_f32_e32 v93, v93
	v_fma_f32 v94, v94, v100, v138
	v_fma_f32 v95, v95, v100, v130
	v_exp_f32_e32 v94, v94
	v_exp_f32_e32 v95, v95
	v_pk_add_f32 v[90:91], v[90:91], s[0:1] op_sel_hi:[1,0]
	v_fma_f32 v96, v96, v100, v123
	v_fma_f32 v97, v97, v100, v124
	v_rcp_f32_e32 v90, v90
	v_exp_f32_e32 v96, v96
	v_exp_f32_e32 v97, v97
	v_pk_add_f32 v[92:93], v[92:93], s[0:1] op_sel_hi:[1,0]
	v_rcp_f32_e32 v91, v91
	v_rcp_f32_e32 v92, v92
	v_pk_add_f32 v[94:95], v[94:95], s[0:1] op_sel_hi:[1,0]
	v_max_f32_e32 v90, 1.0, v90
	v_rcp_f32_e32 v94, v94
	v_pk_add_f32 v[96:97], v[96:97], s[0:1] op_sel_hi:[1,0]
	v_cvt_pk_u8_f32 v90, v90, 0, 0
	v_rcp_f32_e32 v95, v95
	v_max_f32_e32 v91, 1.0, v91
	v_cvt_pk_u8_f32 v90, v91, 1, v90
	v_rcp_f32_e32 v91, v96
	v_max_f32_e32 v92, 1.0, v92
	v_rcp_f32_e32 v93, v93
	v_cvt_pk_u8_f32 v90, v92, 2, v90
	v_rcp_f32_e32 v92, v97
	v_max_f32_e32 v94, 1.0, v94
	v_cvt_pk_u8_f32 v94, v94, 0, 0
	v_max_f32_e32 v95, 1.0, v95
	v_cvt_pk_u8_f32 v94, v95, 1, v94
	v_max_f32_e32 v91, 1.0, v91
	v_max_f32_e32 v93, 1.0, v93
	s_mov_b32 s30, 0x1000
	v_cvt_pk_u8_f32 v91, v91, 2, v94
	v_max_f32_e32 v92, 1.0, v92
	v_cvt_pk_u8_f32 v93, v93, 3, v90
	v_add_co_u32_e32 v90, vcc, s30, v148
	v_cvt_pk_u8_f32 v92, v92, 3, v91
	s_nop 0
	v_addc_co_u32_e32 v91, vcc, 0, v149, vcc
	global_store_dwordx2 v[90:91], v[92:93], off
	v_mul_f32_e32 v92, 0xbfb8aa3b, v163
	v_fma_f32 v82, v82, v92, v126
	v_fma_f32 v83, v83, v92, v127
	v_exp_f32_e32 v82, v82
	v_exp_f32_e32 v83, v83
	v_fma_f32 v84, v84, v92, v128
	v_fma_f32 v85, v85, v92, v129
	v_exp_f32_e32 v84, v84
	v_exp_f32_e32 v85, v85
	v_fma_f32 v86, v86, v92, v138
	v_fma_f32 v87, v87, v92, v130
	v_exp_f32_e32 v86, v86
	v_exp_f32_e32 v87, v87
	v_pk_add_f32 v[82:83], v[82:83], s[0:1] op_sel_hi:[1,0]
	v_fma_f32 v88, v88, v92, v123
	v_fma_f32 v89, v89, v92, v124
	v_rcp_f32_e32 v82, v82
	v_exp_f32_e32 v88, v88
	v_exp_f32_e32 v89, v89
	v_pk_add_f32 v[84:85], v[84:85], s[0:1] op_sel_hi:[1,0]
	v_rcp_f32_e32 v83, v83
	v_rcp_f32_e32 v84, v84
	v_pk_add_f32 v[86:87], v[86:87], s[0:1] op_sel_hi:[1,0]
	v_max_f32_e32 v82, 1.0, v82
	v_rcp_f32_e32 v86, v86
	v_pk_add_f32 v[88:89], v[88:89], s[0:1] op_sel_hi:[1,0]
	v_cvt_pk_u8_f32 v82, v82, 0, 0
	v_rcp_f32_e32 v87, v87
	v_max_f32_e32 v83, 1.0, v83
	v_cvt_pk_u8_f32 v82, v83, 1, v82
	v_rcp_f32_e32 v83, v88
	v_max_f32_e32 v84, 1.0, v84
	v_rcp_f32_e32 v85, v85
	v_cvt_pk_u8_f32 v82, v84, 2, v82
	v_rcp_f32_e32 v84, v89
	v_max_f32_e32 v86, 1.0, v86
	v_cvt_pk_u8_f32 v86, v86, 0, 0
	v_max_f32_e32 v87, 1.0, v87
	v_cvt_pk_u8_f32 v86, v87, 1, v86
	v_max_f32_e32 v83, 1.0, v83
	v_max_f32_e32 v85, 1.0, v85
	s_mov_b32 s30, 0x1400
	v_cvt_pk_u8_f32 v83, v83, 2, v86
	v_max_f32_e32 v84, 1.0, v84
	v_cvt_pk_u8_f32 v85, v85, 3, v82
	v_add_co_u32_e32 v82, vcc, s30, v148
	v_cvt_pk_u8_f32 v84, v84, 3, v83
	s_nop 0
	v_addc_co_u32_e32 v83, vcc, 0, v149, vcc
	global_store_dwordx2 v[82:83], v[84:85], off
	v_mul_f32_e32 v84, 0xbfb8aa3b, v161
	v_fma_f32 v74, v74, v84, v126
	v_fma_f32 v75, v75, v84, v127
	v_exp_f32_e32 v74, v74
	v_exp_f32_e32 v75, v75
	v_fma_f32 v76, v76, v84, v128
	v_fma_f32 v77, v77, v84, v129
	v_exp_f32_e32 v76, v76
	v_exp_f32_e32 v77, v77
	v_fma_f32 v78, v78, v84, v138
	v_fma_f32 v79, v79, v84, v130
	v_exp_f32_e32 v78, v78
	v_exp_f32_e32 v79, v79
	v_pk_add_f32 v[74:75], v[74:75], s[0:1] op_sel_hi:[1,0]
	v_fma_f32 v80, v80, v84, v123
	v_fma_f32 v81, v81, v84, v124
	v_rcp_f32_e32 v74, v74
	v_exp_f32_e32 v80, v80
	v_exp_f32_e32 v81, v81
	v_pk_add_f32 v[76:77], v[76:77], s[0:1] op_sel_hi:[1,0]
	v_rcp_f32_e32 v75, v75
	v_rcp_f32_e32 v76, v76
	v_pk_add_f32 v[78:79], v[78:79], s[0:1] op_sel_hi:[1,0]
	v_max_f32_e32 v74, 1.0, v74
	v_rcp_f32_e32 v78, v78
	v_pk_add_f32 v[80:81], v[80:81], s[0:1] op_sel_hi:[1,0]
	v_cvt_pk_u8_f32 v74, v74, 0, 0
	v_rcp_f32_e32 v79, v79
;     template <int QVV> __device__ __forceinline__ void run(f32x4 (&acc)[2][2][4][2], const Unit& u, int wr, int wc, int fr, int fq) const {
;     ...
;             const f32x4 s0 = (*(const f32x4*)(swb + co + bj * HALF * 4) + *(const f32x4*)(bmb + co + bj * HALF * 4)) * (-LOG2E) - 7.994353436858858f,
;                         s1 = (*(const f32x4*)(swb + co + bj * HALF * 4 + 16) + *(const f32x4*)(bmb + co + bj * HALF * 4 + 16)) * (-LOG2E) - 7.994353436858858f;
; #pragma unroll
;             for (int ai = 0; ai < 2; ++ai)
; #pragma unroll
;                 for (int m = 0; m < 4; ++m) { if (ai >= nai) continue;
;                     const float rn = rs[ai][m] * (-LOG2E);
;                     const f32x4 x0 = acc[ai][bj][m][0] * rn + s0, x1 = acc[ai][bj][m][1] * rn + s1;
;                     f32x4 d0, d1;
; #pragma unroll
;                     for (int i = 0; i < 4; ++i) { d0[i] = __builtin_amdgcn_exp2f(x0[i]); d1[i] = __builtin_amdgcn_exp2f(x1[i]); }
;                     d0 = d0 + (1.0f / 255.0f); d1 = d1 + (1.0f / 255.0f);
;                     u32x2 w = {0u, 0u};
; #pragma unroll
;                     for (int i = 0; i < 4; ++i) { const float g0 = fmaxf(__builtin_amdgcn_rcpf(d0[i]), 1.0f), g1 = fmaxf(__builtin_amdgcn_rcpf(d1[i]), 1.0f);
;                         w.x = __builtin_amdgcn_cvt_pk_u8_f32(g0, i, w.x); w.y = __builtin_amdgcn_cvt_pk_u8_f32(g1, i, w.y); }
;                     *(u32x2*)(tb + lo + (unsigned)((ai * HALF + m * 16) * NGC + bj * HALF)) = w; }
	v_max_f32_e32 v75, 1.0, v75
	v_cvt_pk_u8_f32 v74, v75, 1, v74
	v_rcp_f32_e32 v75, v80
	v_max_f32_e32 v76, 1.0, v76
	v_rcp_f32_e32 v77, v77
	v_cvt_pk_u8_f32 v74, v76, 2, v74
	v_rcp_f32_e32 v76, v81
	v_max_f32_e32 v78, 1.0, v78
	v_cvt_pk_u8_f32 v78, v78, 0, 0
	v_max_f32_e32 v79, 1.0, v79
	v_cvt_pk_u8_f32 v78, v79, 1, v78
	v_max_f32_e32 v75, 1.0, v75
	v_max_f32_e32 v77, 1.0, v77
	s_mov_b32 s30, 0x1800
	v_cvt_pk_u8_f32 v75, v75, 2, v78
	v_max_f32_e32 v76, 1.0, v76
	v_cvt_pk_u8_f32 v77, v77, 3, v74
	v_add_co_u32_e32 v74, vcc, s30, v148
	v_cvt_pk_u8_f32 v76, v76, 3, v75
	s_nop 0
	v_addc_co_u32_e32 v75, vcc, 0, v149, vcc
	global_store_dwordx2 v[74:75], v[76:77], off
	v_mul_f32_e32 v76, 0xbfb8aa3b, v160
	v_fmac_f32_e32 v126, v66, v76
	v_fmac_f32_e32 v127, v67, v76
	v_exp_f32_e32 v66, v126
	v_exp_f32_e32 v67, v127
	v_fmac_f32_e32 v128, v68, v76
	v_fmac_f32_e32 v129, v69, v76
	v_exp_f32_e32 v68, v128
	v_exp_f32_e32 v69, v129
	v_fmac_f32_e32 v138, v70, v76
	v_fmac_f32_e32 v130, v71, v76
	v_exp_f32_e32 v70, v138
	v_exp_f32_e32 v71, v130
	v_pk_add_f32 v[66:67], v[66:67], s[0:1] op_sel_hi:[1,0]
	v_fmac_f32_e32 v123, v72, v76
	v_fmac_f32_e32 v124, v73, v76
	v_rcp_f32_e32 v66, v66
	v_exp_f32_e32 v72, v123
	v_exp_f32_e32 v73, v124
	v_pk_add_f32 v[68:69], v[68:69], s[0:1] op_sel_hi:[1,0]
	v_rcp_f32_e32 v67, v67
	v_rcp_f32_e32 v68, v68
	v_pk_add_f32 v[70:71], v[70:71], s[0:1] op_sel_hi:[1,0]
	v_max_f32_e32 v66, 1.0, v66
	v_rcp_f32_e32 v70, v70
	v_pk_add_f32 v[72:73], v[72:73], s[0:1] op_sel_hi:[1,0]
	v_cvt_pk_u8_f32 v66, v66, 0, 0
	v_rcp_f32_e32 v71, v71
	v_max_f32_e32 v67, 1.0, v67
	v_cvt_pk_u8_f32 v66, v67, 1, v66
	v_rcp_f32_e32 v67, v72
	v_max_f32_e32 v68, 1.0, v68
	v_rcp_f32_e32 v69, v69
	v_cvt_pk_u8_f32 v66, v68, 2, v66
	v_rcp_f32_e32 v68, v73
	v_max_f32_e32 v70, 1.0, v70
	v_cvt_pk_u8_f32 v70, v70, 0, 0
	v_max_f32_e32 v71, 1.0, v71
	v_cvt_pk_u8_f32 v70, v71, 1, v70
	v_max_f32_e32 v67, 1.0, v67
	v_max_f32_e32 v69, 1.0, v69
	s_mov_b32 s30, 0x1c00
	v_cvt_pk_u8_f32 v67, v67, 2, v70
	v_max_f32_e32 v68, 1.0, v68
	v_cvt_pk_u8_f32 v69, v69, 3, v66
	v_add_co_u32_e32 v66, vcc, s30, v148
	v_cvt_pk_u8_f32 v133, v133, 3, v125
	v_cvt_pk_u8_f32 v68, v68, 3, v67
	v_addc_co_u32_e32 v67, vcc, 0, v149, vcc
	global_store_dwordx2 v146, v[132:133], s[98:99]
	global_store_dwordx2 v[66:67], v[68:69], off
	s_mov_b64 s[30:31], -1
	s_andn2_b64 vcc, exec, s[38:39]
	s_waitcnt vmcnt(8)
	v_mov_b64_e32 v[70:71], v[198:199]
	v_mov_b64_e32 v[72:73], v[200:201]
	v_mov_b64_e32 v[78:79], v[202:203]
	v_mov_b64_e32 v[80:81], v[204:205]
	v_mov_b64_e32 v[86:87], v[206:207]
	v_mov_b64_e32 v[88:89], v[208:209]
	v_mov_b64_e32 v[94:95], v[210:211]
	v_mov_b64_e32 v[96:97], v[212:213]
	v_add_f32_e32 v68, v78, v94
	v_fmamk_f32 v68, v68, 0xbfb8aa3b, v236
	v_fma_f32 v62, v62, v147, v68
	v_exp_f32_e32 v78, v62
	v_add_f32_e32 v62, v70, v86
	v_fmamk_f32 v62, v62, 0xbfb8aa3b, v236
	v_fma_f32 v58, v58, v147, v62
	v_exp_f32_e32 v70, v58
	v_add_f32_e32 v58, v79, v95
	v_fmamk_f32 v58, v58, 0xbfb8aa3b, v236
	v_fma_f32 v63, v63, v147, v58
	v_exp_f32_e32 v79, v63
	v_add_f32_e32 v63, v71, v87
	v_fmamk_f32 v63, v63, 0xbfb8aa3b, v236
	v_fma_f32 v59, v59, v147, v63
	v_exp_f32_e32 v71, v59
	v_add_f32_e32 v59, v80, v96
	v_fmamk_f32 v59, v59, 0xbfb8aa3b, v236
	v_fma_f32 v64, v64, v147, v59
	v_exp_f32_e32 v80, v64
	v_add_f32_e32 v64, v72, v88
	v_fmamk_f32 v64, v64, 0xbfb8aa3b, v236
	v_fma_f32 v60, v60, v147, v64
	v_exp_f32_e32 v72, v60
	v_add_f32_e32 v60, v81, v97
	v_fmamk_f32 v60, v60, 0xbfb8aa3b, v236
	v_fma_f32 v65, v65, v147, v60
	v_exp_f32_e32 v81, v65
	v_add_f32_e32 v65, v73, v89
	v_fmamk_f32 v65, v65, 0xbfb8aa3b, v236
	v_fma_f32 v50, v50, v122, v62
	v_fma_f32 v51, v51, v122, v63
	v_fma_f32 v42, v42, v116, v62
	v_fma_f32 v43, v43, v116, v63
	v_fma_f32 v34, v34, v108, v62
	v_fma_f32 v35, v35, v108, v63
	v_fma_f32 v26, v26, v100, v62
	v_fma_f32 v27, v27, v100, v63
	v_fma_f32 v18, v18, v92, v62
	v_fma_f32 v19, v19, v92, v63
	v_fma_f32 v10, v10, v84, v62
	v_fma_f32 v11, v11, v84, v63
	v_fmac_f32_e32 v62, v2, v76
	v_fmac_f32_e32 v63, v3, v76
	v_fma_f32 v61, v61, v147, v65
	v_pk_add_f32 v[78:79], v[78:79], s[0:1] op_sel_hi:[1,0]
	v_pk_add_f32 v[70:71], v[70:71], s[0:1] op_sel_hi:[1,0]
	v_exp_f32_e32 v50, v50
	v_exp_f32_e32 v51, v51
	v_exp_f32_e32 v42, v42
	v_exp_f32_e32 v43, v43
	v_exp_f32_e32 v34, v34
	v_exp_f32_e32 v35, v35
	v_exp_f32_e32 v26, v26
	v_exp_f32_e32 v27, v27
	v_exp_f32_e32 v18, v18
	v_exp_f32_e32 v19, v19
	v_exp_f32_e32 v10, v10
	v_exp_f32_e32 v11, v11
	v_exp_f32_e32 v2, v62
	v_exp_f32_e32 v3, v63
	v_exp_f32_e32 v73, v61
	v_rcp_f32_e32 v61, v78
	v_rcp_f32_e32 v69, v70
	v_fma_f32 v52, v52, v122, v64
	v_fma_f32 v53, v53, v122, v65
	v_fma_f32 v44, v44, v116, v64
	v_fma_f32 v45, v45, v116, v65
	v_fma_f32 v36, v36, v108, v64
	v_fma_f32 v37, v37, v108, v65
	v_fma_f32 v28, v28, v100, v64
	v_fma_f32 v29, v29, v100, v65
	v_fma_f32 v20, v20, v92, v64
	v_fma_f32 v21, v21, v92, v65
	v_fma_f32 v12, v12, v84, v64
	v_fma_f32 v13, v13, v84, v65
	v_fmac_f32_e32 v64, v4, v76
	v_fmac_f32_e32 v65, v5, v76
	v_rcp_f32_e32 v70, v79
	v_rcp_f32_e32 v71, v71
	v_exp_f32_e32 v52, v52
	v_exp_f32_e32 v53, v53
	v_exp_f32_e32 v44, v44
	v_exp_f32_e32 v45, v45
	v_exp_f32_e32 v36, v36
	v_exp_f32_e32 v37, v37
	v_exp_f32_e32 v28, v28
	v_exp_f32_e32 v29, v29
	v_exp_f32_e32 v20, v20
	v_exp_f32_e32 v21, v21
	v_exp_f32_e32 v12, v12
	v_exp_f32_e32 v13, v13
	v_exp_f32_e32 v4, v64
	v_exp_f32_e32 v5, v65
	v_fma_f32 v54, v54, v122, v68
	v_fma_f32 v55, v55, v122, v58
	v_fma_f32 v46, v46, v116, v68
	v_fma_f32 v47, v47, v116, v58
	v_fma_f32 v38, v38, v108, v68
	v_fma_f32 v39, v39, v108, v58
	v_fma_f32 v30, v30, v100, v68
	v_fma_f32 v31, v31, v100, v58
;     template <int QVV> __device__ __forceinline__ void run(f32x4 (&acc)[2][2][4][2], const Unit& u, int wr, int wc, int fr, int fq) const {
;     ...
;             for (int ai = 0; ai < 2; ++ai)
; #pragma unroll
;                 for (int m = 0; m < 4; ++m) { if (ai >= nai) continue;
;                     const float rn = rs[ai][m] * (-LOG2E);
;                     const f32x4 x0 = acc[ai][bj][m][0] * rn + s0, x1 = acc[ai][bj][m][1] * rn + s1;
;                     f32x4 d0, d1;
; #pragma unroll
;                     for (int i = 0; i < 4; ++i) { d0[i] = __builtin_amdgcn_exp2f(x0[i]); d1[i] = __builtin_amdgcn_exp2f(x1[i]); }
;                     d0 = d0 + (1.0f / 255.0f); d1 = d1 + (1.0f / 255.0f);
;                     u32x2 w = {0u, 0u};
; #pragma unroll
;                     for (int i = 0; i < 4; ++i) { const float g0 = fmaxf(__builtin_amdgcn_rcpf(d0[i]), 1.0f), g1 = fmaxf(__builtin_amdgcn_rcpf(d1[i]), 1.0f);
;                         w.x = __builtin_amdgcn_cvt_pk_u8_f32(g0, i, w.x); w.y = __builtin_amdgcn_cvt_pk_u8_f32(g1, i, w.y); }
;                     *(u32x2*)(tb + lo + (unsigned)((ai * HALF + m * 16) * NGC + bj * HALF)) = w; }
	v_fma_f32 v22, v22, v92, v68
	v_fma_f32 v23, v23, v92, v58
	v_fma_f32 v14, v14, v84, v68
	v_fma_f32 v15, v15, v84, v58
	v_fmac_f32_e32 v68, v6, v76
	v_fmac_f32_e32 v58, v7, v76
	v_exp_f32_e32 v54, v54
	v_exp_f32_e32 v55, v55
	v_pk_add_f32 v[50:51], v[50:51], s[0:1] op_sel_hi:[1,0]
	v_exp_f32_e32 v46, v46
	v_exp_f32_e32 v47, v47
	v_pk_add_f32 v[42:43], v[42:43], s[0:1] op_sel_hi:[1,0]
	v_exp_f32_e32 v38, v38
	v_exp_f32_e32 v39, v39
	v_pk_add_f32 v[34:35], v[34:35], s[0:1] op_sel_hi:[1,0]
	v_exp_f32_e32 v30, v30
	v_exp_f32_e32 v31, v31
	v_pk_add_f32 v[26:27], v[26:27], s[0:1] op_sel_hi:[1,0]
	v_exp_f32_e32 v22, v22
	v_exp_f32_e32 v23, v23
	v_pk_add_f32 v[18:19], v[18:19], s[0:1] op_sel_hi:[1,0]
	v_exp_f32_e32 v14, v14
	v_exp_f32_e32 v15, v15
	v_pk_add_f32 v[10:11], v[10:11], s[0:1] op_sel_hi:[1,0]
	v_exp_f32_e32 v6, v68
	v_exp_f32_e32 v7, v58
	v_pk_add_f32 v[2:3], v[2:3], s[0:1] op_sel_hi:[1,0]
	v_max_f32_e32 v61, 1.0, v61
	v_max_f32_e32 v69, 1.0, v69
	v_fma_f32 v56, v56, v122, v59
	v_fma_f32 v57, v57, v122, v60
	v_rcp_f32_e32 v50, v50
	v_fma_f32 v48, v48, v116, v59
	v_fma_f32 v49, v49, v116, v60
	v_rcp_f32_e32 v42, v42
	v_fma_f32 v40, v40, v108, v59
	v_fma_f32 v41, v41, v108, v60
	v_rcp_f32_e32 v34, v34
	v_fma_f32 v32, v32, v100, v59
	v_fma_f32 v33, v33, v100, v60
	v_rcp_f32_e32 v26, v26
	v_fma_f32 v24, v24, v92, v59
	v_fma_f32 v25, v25, v92, v60
	v_rcp_f32_e32 v18, v18
	v_fma_f32 v16, v16, v84, v59
	v_fma_f32 v17, v17, v84, v60
	v_rcp_f32_e32 v10, v10
	v_fmac_f32_e32 v59, v8, v76
	v_fmac_f32_e32 v60, v9, v76
	v_rcp_f32_e32 v2, v2
	v_pk_add_f32 v[80:81], v[80:81], s[0:1] op_sel_hi:[1,0]
	v_pk_add_f32 v[72:73], v[72:73], s[0:1] op_sel_hi:[1,0]
	v_cvt_pk_u8_f32 v61, v61, 0, 0
	v_cvt_pk_u8_f32 v69, v69, 0, 0
	v_max_f32_e32 v70, 1.0, v70
	v_max_f32_e32 v71, 1.0, v71
	v_exp_f32_e32 v56, v56
	v_exp_f32_e32 v57, v57
	v_pk_add_f32 v[52:53], v[52:53], s[0:1] op_sel_hi:[1,0]
	v_rcp_f32_e32 v51, v51
	v_exp_f32_e32 v48, v48
	v_exp_f32_e32 v49, v49
	v_pk_add_f32 v[44:45], v[44:45], s[0:1] op_sel_hi:[1,0]
	v_rcp_f32_e32 v43, v43
	v_exp_f32_e32 v40, v40
	v_exp_f32_e32 v41, v41
	v_pk_add_f32 v[36:37], v[36:37], s[0:1] op_sel_hi:[1,0]
	v_rcp_f32_e32 v35, v35
	v_exp_f32_e32 v32, v32
	v_exp_f32_e32 v33, v33
	v_pk_add_f32 v[28:29], v[28:29], s[0:1] op_sel_hi:[1,0]
	v_rcp_f32_e32 v27, v27
	v_exp_f32_e32 v24, v24
	v_exp_f32_e32 v25, v25
	v_pk_add_f32 v[20:21], v[20:21], s[0:1] op_sel_hi:[1,0]
	v_rcp_f32_e32 v19, v19
	v_exp_f32_e32 v16, v16
	v_exp_f32_e32 v17, v17
	v_pk_add_f32 v[12:13], v[12:13], s[0:1] op_sel_hi:[1,0]
	v_rcp_f32_e32 v11, v11
	v_exp_f32_e32 v8, v59
	v_exp_f32_e32 v9, v60
	v_pk_add_f32 v[4:5], v[4:5], s[0:1] op_sel_hi:[1,0]
	v_rcp_f32_e32 v3, v3
	v_cvt_pk_u8_f32 v61, v70, 1, v61
	v_cvt_pk_u8_f32 v69, v71, 1, v69
	v_rcp_f32_e32 v70, v80
	v_rcp_f32_e32 v71, v72
	v_rcp_f32_e32 v52, v52
	v_rcp_f32_e32 v44, v44
	v_rcp_f32_e32 v36, v36
	v_rcp_f32_e32 v28, v28
	v_rcp_f32_e32 v20, v20
	v_rcp_f32_e32 v12, v12
	v_rcp_f32_e32 v4, v4
	v_pk_add_f32 v[54:55], v[54:55], s[0:1] op_sel_hi:[1,0]
	v_pk_add_f32 v[46:47], v[46:47], s[0:1] op_sel_hi:[1,0]
	v_pk_add_f32 v[38:39], v[38:39], s[0:1] op_sel_hi:[1,0]
	v_pk_add_f32 v[30:31], v[30:31], s[0:1] op_sel_hi:[1,0]
	v_pk_add_f32 v[22:23], v[22:23], s[0:1] op_sel_hi:[1,0]
	v_pk_add_f32 v[14:15], v[14:15], s[0:1] op_sel_hi:[1,0]
	v_pk_add_f32 v[6:7], v[6:7], s[0:1] op_sel_hi:[1,0]
	v_rcp_f32_e32 v54, v54
	v_max_f32_e32 v50, 1.0, v50
	v_rcp_f32_e32 v46, v46
	v_max_f32_e32 v42, 1.0, v42
	v_rcp_f32_e32 v38, v38
	v_max_f32_e32 v34, 1.0, v34
	v_rcp_f32_e32 v30, v30
	v_max_f32_e32 v26, 1.0, v26
	v_rcp_f32_e32 v22, v22
	v_max_f32_e32 v18, 1.0, v18
	v_rcp_f32_e32 v14, v14
	v_max_f32_e32 v10, 1.0, v10
	v_rcp_f32_e32 v6, v6
	v_max_f32_e32 v2, 1.0, v2
	v_pk_add_f32 v[56:57], v[56:57], s[0:1] op_sel_hi:[1,0]
	v_cvt_pk_u8_f32 v50, v50, 0, 0
	v_rcp_f32_e32 v55, v55
	v_max_f32_e32 v51, 1.0, v51
	v_pk_add_f32 v[48:49], v[48:49], s[0:1] op_sel_hi:[1,0]
	v_cvt_pk_u8_f32 v42, v42, 0, 0
	v_rcp_f32_e32 v47, v47
	v_max_f32_e32 v43, 1.0, v43
	v_pk_add_f32 v[40:41], v[40:41], s[0:1] op_sel_hi:[1,0]
	v_cvt_pk_u8_f32 v34, v34, 0, 0
	v_rcp_f32_e32 v39, v39
	v_max_f32_e32 v35, 1.0, v35
	v_pk_add_f32 v[32:33], v[32:33], s[0:1] op_sel_hi:[1,0]
	v_cvt_pk_u8_f32 v26, v26, 0, 0
	v_rcp_f32_e32 v31, v31
	v_max_f32_e32 v27, 1.0, v27
	v_pk_add_f32 v[24:25], v[24:25], s[0:1] op_sel_hi:[1,0]
	v_cvt_pk_u8_f32 v18, v18, 0, 0
	v_rcp_f32_e32 v23, v23
	v_max_f32_e32 v19, 1.0, v19
	v_pk_add_f32 v[16:17], v[16:17], s[0:1] op_sel_hi:[1,0]
; #define PG8_BAR __builtin_amdgcn_s_barrier()
;     ...
;         if (wr == 0) PG8_BAR;
;         E.template run<QV>(acc, cur, wr, wc, fr, fq);
;         if (!has_next) break;
;         if (!cur.keep) {
; #pragma unroll
;             for (int a = 0; a < 2; ++a)
; #pragma unroll
;                 for (int b = 0; b < 2; ++b)
; #pragma unroll
;                     for (int m = 0; m < 4; ++m)
; #pragma unroll
;                         for (int n = 0; n < 2; ++n) { f32x2 z0, z1; asm("v_mov_b64 %0, 0\n\tv_mov_b64 %1, 0" : "=v"(z0), "=v"(z1));
;                     acc[a][b][m][n] = __builtin_shufflevector(z0, z1, 0, 1, 2, 3); }
;         }
;         cur = nxt; cA = nA; cB = nB; ++ui;
;         if (wr == 1) PG8_BAR;
;     template <int QVV> __device__ __forceinline__ void run(f32x4 (&acc)[2][2][4][2], const Unit& u, int wr, int wc, int fr, int fq) const {
;     ...
;             for (int ai = 0; ai < 2; ++ai)
; #pragma unroll
;                 for (int m = 0; m < 4; ++m) { if (ai >= nai) continue;
;                     const float rn = rs[ai][m] * (-LOG2E);
;                     const f32x4 x0 = acc[ai][bj][m][0] * rn + s0, x1 = acc[ai][bj][m][1] * rn + s1;
;                     f32x4 d0, d1;
; #pragma unroll
;                     for (int i = 0; i < 4; ++i) { d0[i] = __builtin_amdgcn_exp2f(x0[i]); d1[i] = __builtin_amdgcn_exp2f(x1[i]); }
;                     d0 = d0 + (1.0f / 255.0f); d1 = d1 + (1.0f / 255.0f);
;                     u32x2 w = {0u, 0u};
; #pragma unroll
;                     for (int i = 0; i < 4; ++i) { const float g0 = fmaxf(__builtin_amdgcn_rcpf(d0[i]), 1.0f), g1 = fmaxf(__builtin_amdgcn_rcpf(d1[i]), 1.0f);
;                         w.x = __builtin_amdgcn_cvt_pk_u8_f32(g0, i, w.x); w.y = __builtin_amdgcn_cvt_pk_u8_f32(g1, i, w.y); }
;                     *(u32x2*)(tb + lo + (unsigned)((ai * HALF + m * 16) * NGC + bj * HALF)) = w; }
	v_cvt_pk_u8_f32 v10, v10, 0, 0
	v_rcp_f32_e32 v15, v15
	v_max_f32_e32 v11, 1.0, v11
	v_pk_add_f32 v[8:9], v[8:9], s[0:1] op_sel_hi:[1,0]
	v_cvt_pk_u8_f32 v2, v2, 0, 0
	v_rcp_f32_e32 v7, v7
	v_max_f32_e32 v3, 1.0, v3
	v_max_f32_e32 v70, 1.0, v70
	v_max_f32_e32 v71, 1.0, v71
	v_cvt_pk_u8_f32 v50, v51, 1, v50
	v_rcp_f32_e32 v51, v56
	v_max_f32_e32 v52, 1.0, v52
	v_cvt_pk_u8_f32 v42, v43, 1, v42
	v_rcp_f32_e32 v43, v48
	v_max_f32_e32 v44, 1.0, v44
	v_cvt_pk_u8_f32 v34, v35, 1, v34
	v_rcp_f32_e32 v35, v40
	v_max_f32_e32 v36, 1.0, v36
	v_cvt_pk_u8_f32 v26, v27, 1, v26
	v_rcp_f32_e32 v27, v32
	v_max_f32_e32 v28, 1.0, v28
	v_cvt_pk_u8_f32 v18, v19, 1, v18
	v_rcp_f32_e32 v19, v24
	v_max_f32_e32 v20, 1.0, v20
	v_cvt_pk_u8_f32 v10, v11, 1, v10
	v_rcp_f32_e32 v11, v16
	v_max_f32_e32 v12, 1.0, v12
	v_cvt_pk_u8_f32 v2, v3, 1, v2
	v_rcp_f32_e32 v3, v8
	v_max_f32_e32 v4, 1.0, v4
	v_cvt_pk_u8_f32 v61, v70, 2, v61
	v_cvt_pk_u8_f32 v69, v71, 2, v69
	v_rcp_f32_e32 v70, v81
	v_rcp_f32_e32 v71, v73
	v_cvt_pk_u8_f32 v52, v52, 2, v50
	v_rcp_f32_e32 v50, v57
	v_rcp_f32_e32 v53, v53
	v_cvt_pk_u8_f32 v44, v44, 2, v42
	v_rcp_f32_e32 v42, v49
	v_rcp_f32_e32 v45, v45
	v_cvt_pk_u8_f32 v36, v36, 2, v34
	v_rcp_f32_e32 v34, v41
	v_rcp_f32_e32 v37, v37
	v_cvt_pk_u8_f32 v28, v28, 2, v26
	v_rcp_f32_e32 v26, v33
	v_rcp_f32_e32 v29, v29
	v_cvt_pk_u8_f32 v20, v20, 2, v18
	v_rcp_f32_e32 v18, v25
	v_rcp_f32_e32 v21, v21
	v_cvt_pk_u8_f32 v12, v12, 2, v10
	v_rcp_f32_e32 v10, v17
	v_rcp_f32_e32 v13, v13
	v_cvt_pk_u8_f32 v4, v4, 2, v2
	v_rcp_f32_e32 v2, v9
	v_rcp_f32_e32 v5, v5
	v_max_f32_e32 v54, 1.0, v54
	v_max_f32_e32 v46, 1.0, v46
	v_max_f32_e32 v38, 1.0, v38
	v_max_f32_e32 v30, 1.0, v30
	v_max_f32_e32 v22, 1.0, v22
	v_max_f32_e32 v14, 1.0, v14
	v_max_f32_e32 v6, 1.0, v6
	v_cvt_pk_u8_f32 v54, v54, 0, 0
	v_max_f32_e32 v55, 1.0, v55
	v_cvt_pk_u8_f32 v46, v46, 0, 0
	v_max_f32_e32 v47, 1.0, v47
	v_cvt_pk_u8_f32 v38, v38, 0, 0
	v_max_f32_e32 v39, 1.0, v39
	v_cvt_pk_u8_f32 v30, v30, 0, 0
	v_max_f32_e32 v31, 1.0, v31
	v_cvt_pk_u8_f32 v22, v22, 0, 0
	v_max_f32_e32 v23, 1.0, v23
	v_cvt_pk_u8_f32 v14, v14, 0, 0
	v_max_f32_e32 v15, 1.0, v15
	v_cvt_pk_u8_f32 v6, v6, 0, 0
	v_max_f32_e32 v7, 1.0, v7
	v_cvt_pk_u8_f32 v54, v55, 1, v54
	v_max_f32_e32 v51, 1.0, v51
	v_cvt_pk_u8_f32 v46, v47, 1, v46
	v_max_f32_e32 v43, 1.0, v43
	v_cvt_pk_u8_f32 v38, v39, 1, v38
	v_max_f32_e32 v35, 1.0, v35
	v_cvt_pk_u8_f32 v30, v31, 1, v30
	v_max_f32_e32 v27, 1.0, v27
	v_cvt_pk_u8_f32 v22, v23, 1, v22
	v_max_f32_e32 v19, 1.0, v19
	v_cvt_pk_u8_f32 v14, v15, 1, v14
	v_max_f32_e32 v11, 1.0, v11
	v_cvt_pk_u8_f32 v6, v7, 1, v6
	v_max_f32_e32 v3, 1.0, v3
	v_max_f32_e32 v70, 1.0, v70
	v_max_f32_e32 v71, 1.0, v71
	v_cvt_pk_u8_f32 v51, v51, 2, v54
	v_max_f32_e32 v50, 1.0, v50
	v_max_f32_e32 v53, 1.0, v53
	v_cvt_pk_u8_f32 v43, v43, 2, v46
	v_max_f32_e32 v42, 1.0, v42
	v_max_f32_e32 v45, 1.0, v45
	v_cvt_pk_u8_f32 v35, v35, 2, v38
	v_max_f32_e32 v34, 1.0, v34
	v_max_f32_e32 v37, 1.0, v37
	v_cvt_pk_u8_f32 v27, v27, 2, v30
	v_max_f32_e32 v26, 1.0, v26
	v_max_f32_e32 v29, 1.0, v29
	v_cvt_pk_u8_f32 v19, v19, 2, v22
	v_max_f32_e32 v18, 1.0, v18
	v_max_f32_e32 v21, 1.0, v21
	v_cvt_pk_u8_f32 v11, v11, 2, v14
	v_max_f32_e32 v10, 1.0, v10
	v_max_f32_e32 v13, 1.0, v13
	v_cvt_pk_u8_f32 v3, v3, 2, v6
	v_max_f32_e32 v2, 1.0, v2
	v_max_f32_e32 v5, 1.0, v5
	v_cvt_pk_u8_f32 v70, v70, 3, v61
	v_cvt_pk_u8_f32 v71, v71, 3, v69
	v_cvt_pk_u8_f32 v50, v50, 3, v51
	v_cvt_pk_u8_f32 v51, v53, 3, v52
	v_cvt_pk_u8_f32 v42, v42, 3, v43
	v_cvt_pk_u8_f32 v43, v45, 3, v44
	v_cvt_pk_u8_f32 v34, v34, 3, v35
	v_cvt_pk_u8_f32 v35, v37, 3, v36
	v_cvt_pk_u8_f32 v26, v26, 3, v27
	v_cvt_pk_u8_f32 v27, v29, 3, v28
	v_cvt_pk_u8_f32 v18, v18, 3, v19
	v_cvt_pk_u8_f32 v19, v21, 3, v20
	v_cvt_pk_u8_f32 v10, v10, 3, v11
	v_cvt_pk_u8_f32 v11, v13, 3, v12
	v_cvt_pk_u8_f32 v2, v2, 3, v3
	v_cvt_pk_u8_f32 v3, v5, 3, v4
	global_store_dwordx2 v146, v[70:71], s[98:99] offset:128
	global_store_dwordx2 v[114:115], v[50:51], off offset:128
	global_store_dwordx2 v[106:107], v[42:43], off offset:128
	global_store_dwordx2 v[98:99], v[34:35], off offset:128
	global_store_dwordx2 v[90:91], v[26:27], off offset:128
	global_store_dwordx2 v[82:83], v[18:19], off offset:128
	global_store_dwordx2 v[74:75], v[10:11], off offset:128
	global_store_dwordx2 v[66:67], v[2:3], off offset:128
	s_cbranch_vccnz .LBB0_1270
	s_andn2_b64 vcc, exec, s[48:49]
	v_mov_b64 v[2:3], 0
	v_mov_b64 v[4:5], 0
	s_cbranch_vccnz .LBB0_1269
	s_barrier
	s_branch .LBB0_1269
